# loop-edge: attention early-store wait/group selection laid out so the common case falls through (rare cases out of line, in-loop byte size preserved)
# baseline (speedup 1.0000x reference)
; #define AT_LOAD(t, K_, R_, V_) do { K_ = *(const u32x4*)(ksrc + (size_t)(t) * 64 * 512); if (tid < 256) R_ = *(const u32x4*)(rsrc + (size_t)(t) * 64 * 32); V_ = *(const u32x4*)(vsrc + (size_t)(t) * 64); } while (0)
; #define AT_STORE(t, K_, R_, V_) do { LAS unsigned char* sk = lds + AT_K0 + ((t) & 1) * KT_BYTES; *(LAS u32x4*)(sk + kdst) = K_; if (tid < 256) *(LAS u32x4*)(sk + rdst) = R_; \
;         LAS unsigned char* sv = lds + ((t) & 1) * VT_BYTES; *(LAS u32x2*)(sv + vdst) = (u32x2){V_.x, V_.y}; *(LAS u32x2*)(sv + vdst + 16) = (u32x2){V_.z, V_.w}; } while (0)
; #define AT_BAR() asm volatile("s_waitcnt lgkmcnt(0)\n\ts_barrier" ::: "memory")
; __device__ __forceinline__ void attn_unit(const Ctx& C, int qrow0, int krow0, int h, int NT, int ntw) {
;     ...
;     for (; t + 1 < NT; t += 2) {
;         if (t + 2 < NT) AT_LOAD(t + 2, kB, rB, vB);
;         if (t < ntw) at_step<false>(o0, o1, negm, mrun, lrun, qr, Kl + KT_BYTES, Vl + VT_BYTES);
;         AT_STORE(t + 1, kA, rA, vA);
;         AT_BAR();
;         if (t + 3 < NT) AT_LOAD(t + 3, kA, rA, vA);
;         if (t + 1 < ntw) at_step<false>(o0, o1, negm, mrun, lrun, qr, Kl, Vl);
;         if (t + 2 < NT) AT_STORE(t + 2, kB, rB, vB);
;         AT_BAR();
;     }
.LBB0_1190:
	s_cmp_lg_u64 s[60:61], 0
	s_cbranch_scc0 .Lst1_r
	s_waitcnt vmcnt(3)
	s_mov_b32 s99, 0x12345678
.Lst1_b:
	ds_write_b128 v155, v[124:127]
	s_cmp_lg_u32 s98, 0
	s_cbranch_scc1 .Lst1_hr
	ds_write_b128 v160, v[108:111] offset:128
	s_mov_b32 s99, 0x12345678

; #define AT_STORE(t, K_, R_, V_) do { LAS unsigned char* sk = lds + AT_K0 + ((t) & 1) * KT_BYTES; *(LAS u32x4*)(sk + kdst) = K_; if (tid < 256) *(LAS u32x4*)(sk + rdst) = R_; \
;         LAS unsigned char* sv = lds + ((t) & 1) * VT_BYTES; *(LAS u32x2*)(sv + vdst) = (u32x2){V_.x, V_.y}; *(LAS u32x2*)(sv + vdst + 16) = (u32x2){V_.z, V_.w}; } while (0)
; __device__ __forceinline__ void attn_unit(const Ctx& C, int qrow0, int krow0, int h, int NT, int ntw) {
;     ...
;         if (t + 2 < NT) AT_STORE(t + 2, kB, rB, vB);
.LBB0_1196:
	s_cmp_lg_u64 s[60:61], 0
	s_cbranch_scc0 .Lst2_none
	s_cmp_lg_u64 s[62:63], 0
	s_cbranch_scc1 .Lst2_r
	s_waitcnt vmcnt(3)
	s_mov_b32 s99, 0x12345678
.Lst2_b:
	ds_write_b128 v155, v[112:115] offset:13312
	s_cmp_lg_u32 s98, 0
	s_cbranch_scc1 .Lst2_hr
	ds_write_b128 v160, v[116:119] offset:13440
	s_mov_b32 s99, 0x12345678

.Lst1_r:
	s_waitcnt vmcnt(0)
	s_branch .Lst1_b
.Lst1_hr:
	s_waitcnt vmcnt(2)
	s_branch .Lst1_v
